# static priority raise (s_setprio 1) for waves 0-3 during phase E, reset at phase exit
# baseline (speedup 1.0000x reference)
; DI void phaseE(int wv0, PP p, unsigned char* smem, int cidx) {
;   __shared__ int s_item;
;   int* ctr = (int*)(p->ws + OFF_CTR) + cidx;
;   for (;;) {
;     __syncthreads();
;     if (my_tid(wv0) == 0) s_item = atomicAdd(ctr, 1);
;     __syncthreads();
;     const int item = s_item;
;     if (item >= 1024 + 2048 + (NXT - NXT_A)) break;
;     if (item < 1024) nsa_item(wv0, p, item, smem);
;     else if (item < 1024 + 2048) s5_item<true>(wv0, p, item - 1024, smem);
;     else xpose_tile(wv0, p, NXT_A + (item - 3072), smem);
;   }
; }
.LBB0_722:
	s_cmp_lt_u32 s89, 4
	s_cbranch_scc0 .Lmy_prio_done
	s_setprio 1
